# P3: the 128 workgroups without a scan item run the weight-transposes queue first (while the others scan), then attention; v010 base
# speedup vs baseline: 1.0089x; 1.0051x over previous
; DI int v_rd_base(int lane) { return ((lane & 3) << 3) | (((lane >> 2) & 3) << 6) | (((lane >> 4) & 1) << 5) | (((lane >> 5) & 1) << 8); }
; template <int VAR> DI void scan_item(int b, int h, int dir, const u16* __restrict__ KKb, const u16* __restrict__ RI, const u16* __restrict__ RQ, u16* __restrict__ OUT, char* lds) {
;   int tid_ = threadIdx.x; asm volatile("" : "+v"(tid_)); const int tid = tid_, wid = __builtin_amdgcn_readfirstlane(tid >> 6), lane = tid & 63, r32 = lane & 31, hi = lane >> 5;
;   const int k0 = 2 * lane, seg = wid;
;   const int tb = wid >> 2, vb = wid & 3, kb0 = 2 * (wid >> 2);
;   const int colh = h * 128;
;   float* TOT = (float*)(lds + SC_TOT); float* BEND = (float*)(lds + SC_BEND);
;   const int lbase = (int)(uintptr_t)lds;
;   const int rdb = v_rd_base(lane);
;   f32x16 s0 = {}, s1 = {};
;   { u32x4v z = {0u, 0u, 0u, 0u}; *(u32x4v*)(lds + SC_SS + tid * 64) = z; *(u32x4v*)(lds + SC_SS + tid * 64 + 16) = z; *(u32x4v*)(lds + SC_SS + tid * 64 + 32) = z; *(u32x4v*)(lds + SC_SS + tid * 64 + 48) = z; }
;   const int sr = tid >> 4, sc = (tid & 15) * 8;
;   unsigned gr[8], qv[8]; s16x8 vr0, vr1;
;     ...
;   SC_LOAD(0);
; __global__ void __launch_bounds__(512, 2) fwd_megakernel(Params p_unused) {
;     ...
;     if (bx < 128) { const int b = bx >> 4, h = (bx >> 1) & 7, dir = bx & 1;
;     ...
;       if (rep == 1) scan_item<PROBE_SCANVAR>(b, h, dir, dir ? LFB : LFF, RI, RQ, (u16*)(ws + 196 * MiB), lds); else
;     ...
;       scan_item<0>(b, h, dir, dir ? LFB : LFF, RI, RQ, dir ? OB : OF, lds);
.LBB0_270:
	s_or_b64 exec, exec, s[4:5]
	s_mov_b64 s[0:1], s[86:87]
	s_waitcnt lgkmcnt(0)
	s_barrier
	s_load_dwordx2 s[94:95], s[0:1], 0x60
	s_load_dwordx8 s[4:11], s[0:1], 0x70
	s_load_dwordx2 s[70:71], s[0:1], 0x98
	s_load_dwordx2 s[82:83], s[0:1], 0xb0
	s_load_dwordx2 s[90:91], s[0:1], 0xc8
	v_mov_b32_e32 v196, v194
	s_mov_b32 s100, 0
	s_cmpk_gt_i32 s96, 0x7f
	s_waitcnt lgkmcnt(0)
	v_writelane_b32 v247, s4, 5
	v_readfirstlane_b32 s72, v196
	s_nop 0
	v_writelane_b32 v247, s5, 6
	v_writelane_b32 v247, s6, 7
	v_writelane_b32 v247, s7, 8
	v_writelane_b32 v247, s8, 9
	v_writelane_b32 v247, s9, 10
	v_writelane_b32 v247, s10, 11
	v_writelane_b32 v247, s11, 12
	s_cbranch_scc1 .Lxp_early
	v_mov_b32_e32 v16, v194
	s_and_b32 s1, s96, 1
	v_readfirstlane_b32 s0, v16
	s_ashr_i32 s3, s0, 6
	s_lshl_b32 s2, s3, 3
	s_or_b32 s25, s2, 7
	s_or_b32 s24, s2, 6
	s_sub_i32 s6, 63, s25
	s_cmp_eq_u32 s1, 0
	s_cselect_b64 s[4:5], -1, 0
	s_and_b64 s[4:5], s[4:5], exec
	s_cselect_b32 s11, s25, s6
	s_sub_i32 s6, 63, s24
	s_cmp_eq_u32 s1, 0
	s_cselect_b64 s[4:5], -1, 0
	s_and_b64 s[4:5], s[4:5], exec
	s_cselect_b32 s12, s24, s6
	s_or_b32 s26, s2, 5
	s_sub_i32 s6, 63, s26
	s_cmp_eq_u32 s1, 0
	s_cselect_b64 s[4:5], -1, 0
	s_and_b64 s[4:5], s[4:5], exec
	s_cselect_b32 s13, s26, s6
	s_or_b32 s27, s2, 4
	s_sub_i32 s6, 63, s27
	s_cmp_eq_u32 s1, 0
	s_cselect_b64 s[4:5], -1, 0
	s_and_b64 s[4:5], s[4:5], exec
	s_cselect_b32 s14, s27, s6
	s_or_b32 s28, s2, 3
	s_sub_i32 s6, 63, s28
	s_cmp_eq_u32 s1, 0
	s_cselect_b64 s[4:5], -1, 0
	s_and_b64 s[4:5], s[4:5], exec
	s_cselect_b32 s15, s28, s6
	s_or_b32 s29, s2, 2
	s_sub_i32 s6, 63, s29
	s_cmp_eq_u32 s1, 0
	s_cselect_b64 s[4:5], -1, 0
	s_and_b64 s[4:5], s[4:5], exec
	s_cselect_b32 s16, s29, s6
	s_or_b32 s30, s2, 1
	s_sub_i32 s6, 63, s30
	s_cmp_eq_u32 s1, 0
	s_cselect_b64 s[4:5], -1, 0
	s_and_b64 s[4:5], s[4:5], exec
	s_cselect_b32 s17, s30, s6
	s_sub_i32 s6, 63, s2
	s_cmp_eq_u32 s1, 0
	v_writelane_b32 v247, s72, 13
	s_cselect_b64 s[4:5], -1, 0
	v_writelane_b32 v247, s82, 14
	s_and_b64 s[4:5], s[4:5], exec
	s_cselect_b32 s18, s2, s6
	v_writelane_b32 v247, s83, 15
	s_add_u32 s2, s90, 0x8400000
	v_writelane_b32 v247, s70, 16
	s_addc_u32 s8, s91, 0
	s_add_u32 s9, s90, 0xa400000
	v_writelane_b32 v247, s71, 17
	v_writelane_b32 v247, s81, 18
	s_addc_u32 s10, s91, 0
	v_writelane_b32 v247, s80, 19
	s_cmp_eq_u32 s1, 0
	v_writelane_b32 v247, s74, 20
	s_cselect_b64 s[4:5], -1, 0
	s_and_b64 s[6:7], s[4:5], exec
	v_writelane_b32 v247, s75, 21
	v_writelane_b32 v247, s73, 22
	s_mov_b32 s1, 0x11400000
	s_mov_b32 s7, s96
	v_writelane_b32 v247, s86, 23
	s_cselect_b32 s1, s1, 0x13800000
	s_cselect_b32 s96, s2, s9
	s_cselect_b32 s97, s8, s10
	s_ashr_i32 s2, s7, 4
	s_bfe_i32 s6, s7, 0x10000
	v_writelane_b32 v247, s87, 24
	s_mul_i32 s8, s2, 0x900
	s_and_b32 s6, s6, 0xc0
	v_writelane_b32 v247, s7, 25
	s_lshl_b32 s7, s7, 6
	s_or_b32 s6, s8, s6
	s_and_b32 s31, s7, 0x380
	s_lshl_b32 s2, s2, 11
	s_addk_i32 s6, 0x800
	s_add_u32 s88, s90, 0x18000000
	s_addc_u32 s89, s91, 0
	s_add_u32 s92, s90, 0x15c00000
	s_mov_b32 s60, 0
	s_addc_u32 s93, s91, 0
	v_ashrrev_i32_e32 v17, 4, v16
	s_add_u32 s58, s90, s1
	s_mov_b32 s61, s60
	v_sub_u32_e32 v0, 63, v17
	s_addc_u32 s59, s91, 0
	v_and_b32_e32 v18, 63, v16
	s_add_i32 s9, 0, 0x14000
	s_mov_b32 s62, s60
	s_mov_b32 s63, s60
	v_mov_b64_e32 v[2:3], s[60:61]
	v_cndmask_b32_e64 v116, v0, v17, s[4:5]
	v_lshlrev_b32_e32 v20, 1, v18
	v_lshl_add_u32 v0, v16, 6, s9
	v_mov_b64_e32 v[4:5], s[62:63]
	s_add_i32 s1, s18, s6
	ds_write_b128 v0, v[2:5]
	ds_write_b128 v0, v[2:5] offset:16
	ds_write_b128 v0, v[2:5] offset:32
	ds_write_b128 v0, v[2:5] offset:48
	v_lshl_or_b32 v0, s1, 10, v20
	s_add_i32 s1, s17, s6
	v_or_b32_e32 v76, s31, v0
	v_mov_b32_e32 v77, 0
	v_lshl_or_b32 v2, s1, 10, v20
	s_add_i32 s1, s16, s6
	v_lshl_add_u64 v[0:1], v[76:77], 1, s[58:59]
	v_or_b32_e32 v76, s31, v2
	v_lshl_or_b32 v4, s1, 10, v20
	s_add_i32 s1, s15, s6
	v_lshl_add_u64 v[2:3], v[76:77], 1, s[58:59]
	v_or_b32_e32 v76, s31, v4
	v_lshl_or_b32 v6, s1, 10, v20
	s_add_i32 s1, s14, s6
	v_lshl_add_u64 v[4:5], v[76:77], 1, s[58:59]
	v_or_b32_e32 v76, s31, v6
	v_lshl_or_b32 v8, s1, 10, v20
	s_add_i32 s1, s13, s6
	v_lshl_add_u64 v[6:7], v[76:77], 1, s[58:59]
	v_or_b32_e32 v76, s31, v8
	v_lshl_or_b32 v10, s1, 10, v20
	s_add_i32 s1, s12, s6
	v_lshl_add_u64 v[8:9], v[76:77], 1, s[58:59]
	v_or_b32_e32 v76, s31, v10
	v_lshl_or_b32 v12, s1, 10, v20
	s_add_i32 s1, s11, s6
	v_lshlrev_b32_e32 v22, 4, v16
	v_lshl_add_u64 v[10:11], v[76:77], 1, s[58:59]
	v_or_b32_e32 v76, s31, v12
	v_lshl_or_b32 v14, s1, 10, v20
	v_lshlrev_b32_e32 v21, 3, v18
	v_and_b32_e32 v23, 0xc0, v22
	v_lshl_add_u64 v[12:13], v[76:77], 1, s[58:59]
	v_or_b32_e32 v76, s31, v14
	v_and_b32_e32 v24, 32, v20
	v_and_b32_e32 v25, 0x100, v21
	v_lshlrev_b32_e32 v26, 3, v16
	v_lshl_add_u64 v[14:15], v[76:77], 1, s[58:59]
	global_load_dword v120, v[0:1], off
	global_load_dword v123, v[2:3], off
	global_load_dword v128, v[4:5], off
	global_load_dword v132, v[6:7], off
	global_load_dword v133, v[8:9], off
	global_load_dword v134, v[10:11], off
	global_load_dword v146, v[12:13], off
	global_load_dword v154, v[14:15], off
	v_and_or_b32 v0, v21, 24, v23
	v_or3_b32 v117, v0, v24, v25
	v_and_b32_e32 v0, 0x78, v26
	v_sub_u32_e32 v1, 31, v17
	v_add_u32_e32 v5, 32, v17
	v_cndmask_b32_e64 v118, v1, v5, s[4:5]
	v_add_u32_e32 v1, s6, v116
	v_or_b32_e32 v119, s31, v0
	v_lshl_or_b32 v76, v1, 10, v119
	v_add_u32_e32 v2, s6, v118
	v_lshl_add_u64 v[0:1], v[76:77], 1, s[92:93]
	v_lshl_or_b32 v76, v2, 10, v119
	v_lshl_add_u64 v[2:3], v[76:77], 1, s[92:93]
	global_load_dwordx4 v[32:35], v[0:1], off
	global_load_dwordx4 v[36:39], v[2:3], off
; template <int VAR> DI void scan_item(int b, int h, int dir, const u16* __restrict__ KKb, const u16* __restrict__ RI, const u16* __restrict__ RQ, u16* __restrict__ OUT, char* lds) {
;     ...
;   const int k0 = 2 * lane, seg = wid;
;   const int tb = wid >> 2, vb = wid & 3, kb0 = 2 * (wid >> 2);
;   const int colh = h * 128;
;   float* TOT = (float*)(lds + SC_TOT); float* BEND = (float*)(lds + SC_BEND);
;   const int lbase = (int)(uintptr_t)lds;
;   const int rdb = v_rd_base(lane);
;   f32x16 s0 = {}, s1 = {};
;   { u32x4v z = {0u, 0u, 0u, 0u}; *(u32x4v*)(lds + SC_SS + tid * 64) = z; *(u32x4v*)(lds + SC_SS + tid * 64 + 16) = z; *(u32x4v*)(lds + SC_SS + tid * 64 + 32) = z; *(u32x4v*)(lds + SC_SS + tid * 64 + 48) = z; }
;   const int sr = tid >> 4, sc = (tid & 15) * 8;
;     ...
;     if (VAR != 2 && VAR != 3) { f32x2 pre = {1.f, 1.f}, suf = {1.f, 1.f}, mid = {1.f, 1.f};
; #pragma unroll
;       for (int s_ = 0; s_ < 8; ++s_) { const f32x2 t = *(const f32x2*)(TOT + s_ * 128 + k0);
;         if (s_ < seg) pre = pre * t;
;         if (s_ > seg) suf = suf * t;
;         if (seg <= 3 ? (s_ > seg && s_ <= 3) : (s_ >= 4 && s_ < seg)) mid = mid * t; }
;       if (seg == 7) *(f32x2*)(BEND + k0) = pre * P[7];
;       f32x2 sl = {1.f, 1.f};
; #pragma unroll
;       for (int j = 7; j >= 0; --j) { const int i = 8 * seg + j;
;         const f32x2 khat = kk[j] * (sl * suf);
;         *(unsigned*)(lds + SC_KH + v_st(i, k0)) = cvtpk(khat.x, khat.y);
;         if (!isctx) {
;           const f32x2 qt = q[j] * (pre * P[j]);
;           f32x2 e1, e2;
;           if (seg <= 3) { e2 = sl * mid; e1.x = __builtin_amdgcn_rcpf(fmaxf(e2.x, 1e-30f)); e1.y = __builtin_amdgcn_rcpf(fmaxf(e2.y, 1e-30f)); }
;           else { e1 = mid * P[j]; e2.x = __builtin_amdgcn_rcpf(fmaxf(e1.x, 1e-30f)); e2.y = __builtin_amdgcn_rcpf(fmaxf(e1.y, 1e-30f)); }
;           const f32x2 qp = q[j] * e1, kp = kk[j] * e2;
;           const int o2 = KSWZ(i, k0 * 2);
;           *(unsigned*)(lds + SC_QT + o2) = cvtpk(qt.x, qt.y); *(unsigned*)(lds + SC_QP + o2) = cvtpk(qp.x, qp.y); *(unsigned*)(lds + SC_KP + o2) = cvtpk(kp.x, kp.y); }
;         sl = sl * (1.f - kk[j]); }
;       *(s16x8*)(lds + SC_VV + v_st(sr, sc)) = cv0; *(s16x8*)(lds + SC_VV + v_st(32 + sr, sc)) = cv1; }
;     __syncthreads();
;     if (VAR != 1 && VAR != 3) {
;     if (!isctx) {
;       f32x16 p0 = {}, p1 = {};
;       const int trow = tb * 32 + r32;
	s_lshl_b32 s1, s3, 9
	s_add_i32 s6, 0, 0x1c000
	v_writelane_b32 v247, s8, 26
	s_ashr_i32 s8, s0, 8
	s_and_b32 s35, s3, 3
	s_add_i32 s1, s6, s1
	s_cmp_lt_i32 s3, 4
	v_add_u32_e32 v122, s6, v21
	s_cselect_b64 s[6:7], -1, 0
	s_cmp_gt_i32 s3, 3
	s_cselect_b64 s[76:77], -1, 0
	s_cmp_eq_u32 s3, 7
	v_writelane_b32 v247, s18, 27
	v_add_u32_e32 v121, s1, v21
	s_cselect_b64 s[78:79], -1, 0
	v_and_b32_e32 v3, 0xfffff0, v17
	v_lshlrev_b32_e32 v6, 1, v17
	s_add_i32 s1, 0, 0x10000
	s_add_i32 s10, 0, 0x1d000
	s_lshl_b32 s36, s8, 5
	v_writelane_b32 v247, s17, 28
	v_and_or_b32 v3, v6, 8, v3
	v_lshrrev_b32_e32 v6, 1, v17
	v_and_b32_e32 v8, 3, v17
	s_cmp_eq_u32 s8, 1
	v_writelane_b32 v247, s16, 29
	v_and_or_b32 v6, v6, 4, v8
	s_cselect_b64 s[80:81], -1, 0
	s_cmpk_gt_u32 s0, 0xff
	v_writelane_b32 v247, s15, 30
	s_mov_b32 s83, s13
	s_mov_b32 s82, s12
	v_lshl_add_u32 v6, v6, 6, s1
	v_and_b32_e32 v9, 0xfffff0, v5
	v_lshlrev_b32_e32 v5, 1, v5
	s_cselect_b64 s[12:13], -1, 0
	s_lshl_b32 s1, s35, 9
	v_writelane_b32 v247, s14, 31
	v_and_or_b32 v5, v5, 8, v9
	s_cmp_lg_u32 0, -1
	s_mov_b32 s33, s11
	v_lshrrev_b32_e32 v3, 1, v3
	v_bfe_u32 v7, v26, 5, 2
	v_lshrrev_b32_e32 v5, 1, v5
	v_writelane_b32 v247, s12, 32
	s_cselect_b32 s11, 0, 0
	v_and_b32_e32 v19, 31, v16
	v_or_b32_e32 v3, v3, v7
	v_or_b32_e32 v5, v5, v7
	v_writelane_b32 v247, s13, 33
	s_add_i32 s1, s11, s1
	s_lshl_b32 s12, s35, 13
	s_and_b32 s0, s0, 0xffffff00
	s_lshl_b32 s87, s8, 10
	v_bfe_u32 v4, v16, 5, 1
	v_lshl_add_u32 v3, v3, 9, v6
	v_lshl_add_u32 v5, v5, 9, v6
	v_add_u32_e32 v124, s10, v21
	v_or_b32_e32 v6, s36, v19
	s_add_i32 s1, s1, 0x10000
	s_add_i32 s9, s9, s12
	s_add_i32 s10, s10, s0
	s_add_i32 s11, s11, 0xc000
	s_or_b32 s0, s87, 0x200
	v_lshlrev_b32_e32 v7, 4, v4
	v_lshl_add_u32 v125, v6, 8, 0
	v_lshlrev_b32_e32 v6, 8, v19
	v_lshlrev_b32_e32 v10, 2, v4
	v_lshlrev_b32_e32 v4, 3, v4
	s_cmp_lt_i32 s3, 1
	v_add_u32_e32 v129, s9, v6
	v_lshl_or_b32 v4, s8, 7, v4
	s_cselect_b64 s[8:9], -1, 0
	s_cmp_lt_i32 s3, 0
	v_add_u32_e32 v130, s10, v7
	v_add_u32_e32 v131, s11, v117
	s_cselect_b64 s[10:11], -1, 0
	s_cmp_lt_i32 s3, 2
	s_cselect_b64 s[12:13], -1, 0
	s_cmp_lt_i32 s3, 3
	s_cselect_b64 s[14:15], -1, 0
	s_cmp_lt_i32 s3, 5
	s_cselect_b64 s[16:17], -1, 0
	s_cmp_lt_i32 s3, 6
	s_cselect_b64 s[18:19], -1, 0
	s_cmp_lt_i32 s3, 7
	s_cselect_b64 s[20:21], -1, 0
	s_cmp_lt_i32 s3, 8
	s_cselect_b64 s[22:23], -1, 0
	s_lshl_b32 s38, s3, 11
	s_lshl_b32 s39, s3, 8
	s_lshl_b32 s3, s3, 2
	v_bfe_u32 v0, v16, 4, 2
	s_and_b32 s3, s3, 0x7ffff8
	v_lshlrev_b32_e32 v1, 2, v18
	v_add_u32_e32 v126, 0, v6
	v_lshl_or_b32 v6, v0, 9, s38
	v_or_b32_e32 v0, s3, v0
	s_lshl_b32 s3, s28, 8
	v_bitop3_b32 v15, s3, 48, v1 bitop3:0x36
	s_lshl_b32 s3, s29, 8
	v_bitop3_b32 v16, s3, 32, v1 bitop3:0x36
	s_lshl_b32 s3, s30, 8
	v_and_b32_e32 v9, 0x70, v22
	v_bitop3_b32 v17, s3, 16, v1 bitop3:0x36
	s_movk_i32 s3, 0x80
	s_lshl_b32 s25, s25, 8
	v_mov_b32_e32 v11, 0x70
	v_bitop3_b32 v139, v7, v9, s3 bitop3:0x36
	s_movk_i32 s3, 0xa0
	s_movk_i32 s34, 0xc0
	s_movk_i32 s37, 0x70
	v_bitop3_b32 v11, s25, v11, v1 bitop3:0x36
	s_movk_i32 s25, 0x60
	v_bitop3_b32 v140, v7, v9, s3 bitop3:0x36
	s_movk_i32 s3, 0xe0
	v_bitop3_b32 v135, v7, v22, s37 bitop3:0x78
	v_bitop3_b32 v136, v7, v9, 32 bitop3:0x36
	v_bitop3_b32 v137, v7, v9, 64 bitop3:0x36
	v_bitop3_b32 v138, v7, v9, s25 bitop3:0x36
	v_bitop3_b32 v141, v7, v9, s34 bitop3:0x36
	v_bitop3_b32 v142, v7, v9, s3 bitop3:0x36
	v_or_b32_e32 v7, s36, v10
	v_sub_u32_e32 v127, v19, v10
	v_sub_u32_e32 v10, 63, v7
	v_cndmask_b32_e64 v143, v10, v7, s[4:5]
	v_or_b32_e32 v10, 1, v7
	v_sub_u32_e32 v18, 63, v10
	v_cndmask_b32_e64 v144, v18, v10, s[4:5]
	v_or_b32_e32 v10, 2, v7
	v_sub_u32_e32 v18, 63, v10
	v_cndmask_b32_e64 v145, v18, v10, s[4:5]
	v_or_b32_e32 v10, 3, v7
	v_sub_u32_e32 v18, 63, v10
	v_cndmask_b32_e64 v147, v18, v10, s[4:5]
	v_or_b32_e32 v10, 8, v7
	v_sub_u32_e32 v18, 63, v10
	v_cndmask_b32_e64 v148, v18, v10, s[4:5]
	v_or_b32_e32 v10, 9, v7
	v_sub_u32_e32 v18, 63, v10
	v_cndmask_b32_e64 v149, v18, v10, s[4:5]
	v_or_b32_e32 v10, 10, v7
	v_sub_u32_e32 v18, 63, v10
	v_cndmask_b32_e64 v150, v18, v10, s[4:5]
	v_or_b32_e32 v10, 11, v7
	v_sub_u32_e32 v18, 63, v10
	v_cndmask_b32_e64 v151, v18, v10, s[4:5]
	v_or_b32_e32 v10, 16, v7
	v_sub_u32_e32 v18, 63, v10
	v_cndmask_b32_e64 v152, v18, v10, s[4:5]
	v_or_b32_e32 v10, 17, v7
	v_sub_u32_e32 v18, 63, v10
	v_cndmask_b32_e64 v153, v18, v10, s[4:5]
	v_or_b32_e32 v10, 18, v7
	v_sub_u32_e32 v18, 63, v10
	v_cndmask_b32_e64 v155, v18, v10, s[4:5]
	v_or_b32_e32 v10, 19, v7
	v_sub_u32_e32 v18, 63, v10
	v_cndmask_b32_e64 v156, v18, v10, s[4:5]
	v_or_b32_e32 v10, 24, v7
	v_sub_u32_e32 v18, 63, v10
	v_cndmask_b32_e64 v157, v18, v10, s[4:5]
	v_or_b32_e32 v10, 25, v7
	v_sub_u32_e32 v18, 63, v10
	s_lshl_b32 s24, s24, 8
	v_mov_b32_e32 v12, 0x60
	v_cndmask_b32_e64 v158, v18, v10, s[4:5]
	v_or_b32_e32 v10, 26, v7
	s_and_b32 s39, s39, 0x100
	v_bitop3_b32 v12, s24, v12, v1 bitop3:0x36
	s_lshl_b32 s24, s26, 8
	v_mov_b32_e32 v13, 0x50
	v_sub_u32_e32 v18, 63, v10
	v_or_b32_e32 v7, 27, v7
	v_or_b32_e32 v6, 0x800, v6
	s_add_i32 s39, s39, 0
	s_movk_i32 s26, 0x50
	v_bitop3_b32 v13, s24, v13, v1 bitop3:0x36
	s_lshl_b32 s24, s27, 8
	v_cndmask_b32_e64 v159, v18, v10, s[4:5]
	v_sub_u32_e32 v10, 63, v7
	v_and_b32_e32 v2, 60, v1
	v_and_b32_e32 v8, 48, v22
	v_add_u32_e32 v6, s39, v6
	v_bitop3_b32 v14, s24, 64, v1 bitop3:0x36
	v_lshl_add_u32 v0, v0, 9, s39
	v_or_b32_e32 v1, s38, v1
	v_cndmask_b32_e64 v160, v10, v7, s[4:5]
	v_add_u32_e32 v7, v129, v4
	v_bitop3_b32 v10, v4, v9, 64 bitop3:0x36
	v_bitop3_b32 v18, v4, v9, 16 bitop3:0x36
	v_bitop3_b32 v21, v4, v9, s26 bitop3:0x36
	v_bitop3_b32 v23, v4, v9, 32 bitop3:0x36
	v_bitop3_b32 v24, v4, v9, s25 bitop3:0x36
	v_bitop3_b32 v25, v4, v9, 48 bitop3:0x36
	v_bitop3_b32 v4, v4, v22, s37 bitop3:0x72
	v_lshl_or_b32 v19, s35, 5, v19
	s_waitcnt vmcnt(1)
; template <int VAR> DI void scan_item(int b, int h, int dir, const u16* __restrict__ KKb, const u16* __restrict__ RI, const u16* __restrict__ RQ, u16* __restrict__ OUT, char* lds) {
;     ...
;   f32x16 s0 = {}, s1 = {};
;   { u32x4v z = {0u, 0u, 0u, 0u}; *(u32x4v*)(lds + SC_SS + tid * 64) = z; *(u32x4v*)(lds + SC_SS + tid * 64 + 16) = z; *(u32x4v*)(lds + SC_SS + tid * 64 + 32) = z; *(u32x4v*)(lds + SC_SS + tid * 64 + 48) = z; }
;   const int sr = tid >> 4, sc = (tid & 15) * 8;
;   unsigned gr[8], qv[8]; s16x8 vr0, vr1;
;     ...
;   SC_LOAD(0);
;   for (int step = 0; step < 36; ++step) {
	v_mov_b64_e32 v[66:67], v[34:35]
	s_waitcnt vmcnt(0)
	v_mov_b64_e32 v[70:71], v[38:39]
	v_or_b32_e32 v161, s31, v20
	v_or_b32_e32 v162, s31, v19
	s_mov_b32 s86, -4
	v_add_u32_e32 v163, 0, v11
	v_add_u32_e32 v164, 0, v12
	v_add_u32_e32 v165, 0, v13
	v_add_u32_e32 v166, 0, v14
	v_add_u32_e32 v167, 0, v15
	v_add_u32_e32 v168, 0, v16
	v_add_u32_e32 v169, 0, v17
	v_add_u32_e32 v170, 0, v1
	v_add_u32_e32 v171, v3, v8
	v_add_u32_e32 v172, v5, v8
	v_add_u32_e32 v173, v7, v9
	v_add_u32_e32 v175, v129, v10
	v_add_u32_e32 v176, v129, v18
	v_add_u32_e32 v177, v129, v21
	v_add_u32_e32 v178, v129, v23
	v_add_u32_e32 v179, v129, v24
	v_add_u32_e32 v180, v129, v25
	v_add_u32_e32 v181, v129, v4
	v_add_u32_e32 v182, v6, v2
	v_add_u32_e32 v183, v0, v2
	v_mov_b32_e32 v0, v77
	v_mov_b32_e32 v1, v77
	v_mov_b32_e32 v2, v77
	v_mov_b32_e32 v3, v77
	v_mov_b32_e32 v4, v77
	v_mov_b32_e32 v5, v77
	v_mov_b32_e32 v6, v77
	v_mov_b32_e32 v7, v77
	v_mov_b32_e32 v8, v77
	v_mov_b32_e32 v9, v77
	v_mov_b32_e32 v10, v77
	v_mov_b32_e32 v11, v77
	v_mov_b32_e32 v12, v77
	v_mov_b32_e32 v13, v77
	v_mov_b32_e32 v14, v77
	v_mov_b32_e32 v15, v77
	v_mov_b32_e32 v16, v77
	v_mov_b32_e32 v17, v77
	v_mov_b32_e32 v18, v77
	v_mov_b32_e32 v19, v77
	v_mov_b32_e32 v20, v77
	v_mov_b32_e32 v21, v77
	v_mov_b32_e32 v22, v77
	v_mov_b32_e32 v23, v77
	v_mov_b32_e32 v24, v77
	v_mov_b32_e32 v25, v77
	v_mov_b32_e32 v26, v77
	v_mov_b32_e32 v27, v77
	v_mov_b32_e32 v28, v77
	v_mov_b32_e32 v29, v77
	v_mov_b32_e32 v30, v77
	v_mov_b32_e32 v31, v77
	v_mov_b64_e32 v[64:65], v[32:33]
	v_mov_b64_e32 v[68:69], v[36:37]
	v_mov_b32_e32 v191, v201
	v_mov_b32_e32 v190, v200
	v_mov_b32_e32 v189, v199
	v_mov_b32_e32 v188, v198
	v_mov_b32_e32 v187, v197
	v_mov_b32_e32 v186, v195
	v_mov_b32_e32 v185, v193
	v_mov_b32_e32 v184, v192
	s_branch .LBB0_274

; __global__ void __launch_bounds__(512, 2) fwd_megakernel(Params p_unused) {
;     ...
;       unsigned* tq = (unsigned*)(ctl + C_CTR) + 1120; u16* WUP = (u16*)(ws + WS_WUP);
;       float* scr = (float*)(lds + wave * 16384);
;       for (;;) {
;         if (tid == 0) *(volatile unsigned*)(lds + ATT_CTR) = atomicAdd(tq, 1u);
;         __syncthreads();
;         const unsigned it = *(volatile unsigned*)(lds + ATT_CTR);
;         __syncthreads();
;         if (it >= 1408u + 1216u) break;
;         if (it < 1408u) { transpose_item(p.w_up, DM, FF2, WUP, scr, (int)it * 8 + wave, lane, false, true); continue; }
.Lxp_early:
	v_and_b32_e32 v24, 63, v196
	s_ashr_i32 s0, s72, 6
	v_cmp_eq_u32_e64 s[4:5], 0, v196
	s_add_i32 s29, 0, 0x21000
	s_mov_b32 s100, 0x5a5a5a5a
	s_branch .LBB0_432

; __global__ void __launch_bounds__(512, 2) fwd_megakernel(Params p_unused) {
;     ...
;       for (;;) {
;         if (tid == 0) *(volatile unsigned*)(lds + ATT_CTR) = atomicAdd(tq, 1u);
;         __syncthreads();
;         const unsigned it = *(volatile unsigned*)(lds + ATT_CTR);
;         __syncthreads();
;         if (it >= 1408u + 1216u) break;
;         if (it < 1408u) { transpose_item(p.w_up, DM, FF2, WUP, scr, (int)it * 8 + wave, lane, false, true); continue; }
;         { constexpr int I_BA = 16 * 64, I_OUT = 32 * 64;
;           WSP(WBA, WS_WBA); WSP(WBR, WS_WBR); WSP(WOUT, WS_WOUT); WSP(WDN, WS_WDN);
;           int r = ((int)it - 1408) * 8 + wave;
;           if (r < I_BA) { transpose_item(p.w_branch_attn, 1024, DM, WBA, scr, r, lane, false); continue; } r -= I_BA;
;           if (r < I_BA) { transpose_item(p.w_branch_rec, 1024, DM, WBR, scr, r, lane, false); continue; } r -= I_BA;
;           if (r < I_OUT) { transpose_item(p.w_out, DM, DM, WOUT, scr, r, lane, false); continue; } r -= I_OUT;
;           transpose_item(p.w_down, FF, DM, WDN, scr, r, lane, false); }
;       } }
.LBB0_456:
	s_or_b64 exec, exec, s[10:11]
	s_cmp_eq_u32 s100, 0x5a5a5a5a
	s_cbranch_scc0 .Lxp_normal
	s_mov_b32 s100, 0
	s_branch .LBB0_367

; __global__ void __launch_bounds__(512, 2) fwd_megakernel(Params p_unused) {
	.amdhsa_kernel _Z14fwd_megakernel6Params
		.amdhsa_group_segment_fixed_size 0
		.amdhsa_private_segment_fixed_size 0
		.amdhsa_kernarg_size 464
		.amdhsa_user_sgpr_count 2
		.amdhsa_user_sgpr_dispatch_ptr 0
		.amdhsa_user_sgpr_queue_ptr 0
		.amdhsa_user_sgpr_kernarg_segment_ptr 1
		.amdhsa_user_sgpr_dispatch_id 0
		.amdhsa_user_sgpr_kernarg_preload_length 0
		.amdhsa_user_sgpr_kernarg_preload_offset 0
		.amdhsa_user_sgpr_private_segment_size 0
		.amdhsa_uses_dynamic_stack 0
		.amdhsa_enable_private_segment 0
		.amdhsa_system_sgpr_workgroup_id_x 1
		.amdhsa_system_sgpr_workgroup_id_y 0
		.amdhsa_system_sgpr_workgroup_id_z 0
		.amdhsa_system_sgpr_workgroup_info 0
		.amdhsa_system_vgpr_workitem_id 2
		.amdhsa_next_free_vgpr 248
		.amdhsa_next_free_sgpr 102
		.amdhsa_accum_offset 248
		.amdhsa_reserve_vcc 1
		.amdhsa_float_round_mode_32 0
		.amdhsa_float_round_mode_16_64 0
		.amdhsa_float_denorm_mode_32 3
		.amdhsa_float_denorm_mode_16_64 3
		.amdhsa_dx10_clamp 1
		.amdhsa_ieee_mode 1
		.amdhsa_fp16_overflow 0
		.amdhsa_tg_split 0
		.amdhsa_exception_fp_ieee_invalid_op 0
		.amdhsa_exception_fp_denorm_src 0
		.amdhsa_exception_fp_ieee_div_zero 0
		.amdhsa_exception_fp_ieee_overflow 0
		.amdhsa_exception_fp_ieee_underflow 0
		.amdhsa_exception_fp_ieee_inexact 0
		.amdhsa_exception_int_div_zero 0
	.end_amdhsa_kernel

; __global__ void __launch_bounds__(512, 2) fwd_megakernel(Params p_unused) {
amdhsa.kernels:
  - .agpr_count:     0
    .args:
      - .offset:         0
        .size:           208
        .value_kind:     by_value
      - .offset:         208
        .size:           4
        .value_kind:     hidden_block_count_x
      - .offset:         212
        .size:           4
        .value_kind:     hidden_block_count_y
      - .offset:         216
        .size:           4
        .value_kind:     hidden_block_count_z
      - .offset:         220
        .size:           2
        .value_kind:     hidden_group_size_x
      - .offset:         222
        .size:           2
        .value_kind:     hidden_group_size_y
      - .offset:         224
        .size:           2
        .value_kind:     hidden_group_size_z
      - .offset:         226
        .size:           2
        .value_kind:     hidden_remainder_x
      - .offset:         228
        .size:           2
        .value_kind:     hidden_remainder_y
      - .offset:         230
        .size:           2
        .value_kind:     hidden_remainder_z
      - .offset:         248
        .size:           8
        .value_kind:     hidden_global_offset_x
      - .offset:         256
        .size:           8
        .value_kind:     hidden_global_offset_y
      - .offset:         264
        .size:           8
        .value_kind:     hidden_global_offset_z
      - .offset:         272
        .size:           2
        .value_kind:     hidden_grid_dims
      - .offset:         296
        .size:           8
        .value_kind:     hidden_multigrid_sync_arg
      - .offset:         328
        .size:           4
        .value_kind:     hidden_dynamic_lds_size
    .group_segment_fixed_size: 0
    .kernarg_segment_align: 8
    .kernarg_segment_size: 464
    .language:       OpenCL C
    .language_version:
      - 2
      - 0
    .max_flat_workgroup_size: 512
    .name:           _Z14fwd_megakernel6Params
    .private_segment_fixed_size: 0
    .sgpr_count:     108
    .sgpr_spill_count: 34
    .symbol:         _Z14fwd_megakernel6Params.kd
    .uniform_work_group_size: 1
    .uses_dynamic_stack: false
    .vgpr_count:     248
    .vgpr_spill_count: 0
    .wavefront_size: 64
